# P0 rmsnorm: g_attn fragments loaded once per wave instead of 20 reloads each behind vmcnt(0) (which also drained the row stores): the 20 serialized store/load round trips are gone
# speedup vs baseline: 1.0031x; 1.0008x over previous
; __host__ __device__ __forceinline__ size_t img_off(int row, int col, int nkt) { return ((size_t)((row >> 7) * nkt + (col >> 6)) << 14) + (size_t)lds_byte(row & 127, col & 63); }
; #define GAS __attribute__((address_space(1)))
; __device__ __forceinline__ unsigned pk2(float lo, float hi) { return pg8::cvt_pk_bf16(lo, hi); }
; __device__ __forceinline__ void rms_pair_finish(const RPair& P, const float* g, bf16* obase, float* rs, int m, int lane) {
;     ...
;     for (int j = 0; j < 4; ++j) { const f32x4 gg = gr[64 * j]; v2u o;
;         o.x = pk2(P.v0[j].x * r0 * gg.x, P.v0[j].y * r0 * gg.y); o.y = pk2(P.v0[j].z * r0 * gg.z, P.v0[j].w * r0 * gg.w); *(GAS v2u*)((GAS char*)obase + pg8::img_off(m, 4 * lane + 256 * j, DM / 64)) = o;
;         o.x = pk2(P.v1[j].x * r1 * gg.x, P.v1[j].y * r1 * gg.y); o.y = pk2(P.v1[j].z * r1 * gg.z, P.v1[j].w * r1 * gg.w); *(GAS v2u*)((GAS char*)obase + pg8::img_off(m + 1, 4 * lane + 256 * j, DM / 64)) = o; }
.LBB0_44:
	s_or_b64 exec, exec, s[4:5]
	s_nop 0
	s_lshr_b32 s3, s52, 3
	s_add_i32 s4, s69, s11
	s_ashr_i32 s2, s52, 3
	v_and_or_b32 v140, s3, 14, v155
	s_and_b32 s3, s4, 0x380
	s_lshr_b32 s4, s4, 4
	s_and_b32 s2, s2, -16
	v_or_b32_e32 v141, s3, v156
	v_lshlrev_b32_e32 v144, 10, v140
	s_and_b32 s4, s4, 32
	v_or3_b32 v145, s3, v154, 64
	v_add_u32_e32 v140, s2, v158
	v_bitop3_b32 v162, v141, v144, s4 bitop3:0xde
	v_ashrrev_i32_e32 v141, 31, v140
	v_lshl_add_u64 v[142:143], s[14:15], 0, v[162:163]
	v_bitop3_b32 v162, v145, v144, s4 bitop3:0xde
	v_mul_f32_e32 v133, v2, v130
	v_mul_f32_e32 v139, v3, v130
	v_mul_f32_e32 v147, v4, v130
	v_mul_f32_e32 v150, v5, v130
	v_mul_f32_e32 v151, v10, v131
	v_mul_f32_e32 v152, v11, v131
	v_lshlrev_b64 v[140:141], 14, v[140:141]
	v_lshl_add_u64 v[144:145], s[14:15], 0, v[162:163]
	v_mul_f32_e32 v153, v12, v131
	v_mul_f32_e32 v157, v13, v131
	v_lshl_add_u64 v[148:149], v[142:143], 0, v[140:141]
	v_lshl_add_u64 v[140:141], v[144:145], 0, v[140:141]
	v_add_u32_e32 v138, s2, v138
	s_waitcnt vmcnt(8)
	v_mul_f32_e32 v133, v133, v196
	v_mul_f32_e32 v139, v139, v197
	v_mul_f32_e32 v147, v147, v198
	v_mul_f32_e32 v150, v150, v199
	v_mul_f32_e32 v151, v151, v196
	v_mul_f32_e32 v152, v152, v197
	v_cvt_pk_bf16_f32 v134, v133, v139
	v_cvt_pk_bf16_f32 v135, v147, v150
	v_mul_f32_e32 v136, v153, v198
	v_mul_f32_e32 v137, v157, v199
	global_store_dwordx2 v[148:149], v[134:135], off
	v_cvt_pk_bf16_f32 v134, v151, v152
	v_cvt_pk_bf16_f32 v135, v136, v137
	global_store_dwordx2 v[140:141], v[134:135], off
	s_nop 0
	v_add_u32_e32 v140, s2, v146
	v_ashrrev_i32_e32 v141, 31, v140
	v_mul_f32_e32 v133, v6, v130
	v_mul_f32_e32 v139, v7, v130
	v_mul_f32_e32 v148, v8, v130
	v_mul_f32_e32 v149, v9, v130
	v_mul_f32_e32 v150, v22, v131
	v_mul_f32_e32 v151, v23, v131
	v_lshlrev_b64 v[140:141], 14, v[140:141]
	v_mul_f32_e32 v152, v24, v131
	v_mul_f32_e32 v153, v25, v131
	v_lshl_add_u64 v[146:147], v[142:143], 0, v[140:141]
	v_lshl_add_u64 v[140:141], v[144:145], 0, v[140:141]
	s_nop 0
	v_mul_f32_e32 v133, v133, v202
	v_mul_f32_e32 v139, v139, v203
	v_mul_f32_e32 v148, v148, v204
	v_mul_f32_e32 v149, v149, v205
	v_mul_f32_e32 v150, v150, v202
	v_mul_f32_e32 v151, v151, v203
	v_cvt_pk_bf16_f32 v134, v133, v139
	v_cvt_pk_bf16_f32 v135, v148, v149
	v_mul_f32_e32 v136, v152, v204
	v_mul_f32_e32 v137, v153, v205
	global_store_dwordx2 v[146:147], v[134:135], off
	v_cvt_pk_bf16_f32 v134, v150, v151
	v_cvt_pk_bf16_f32 v135, v136, v137
	global_store_dwordx2 v[140:141], v[134:135], off
	s_nop 0
	v_ashrrev_i32_e32 v139, 31, v138
	v_mul_f32_e32 v133, v14, v130
	v_mul_f32_e32 v146, v15, v130
	v_mul_f32_e32 v147, v16, v130
	v_mul_f32_e32 v148, v17, v130
	v_mul_f32_e32 v149, v34, v131
	v_mul_f32_e32 v150, v35, v131
	v_lshlrev_b64 v[138:139], 14, v[138:139]
	v_mul_f32_e32 v151, v36, v131
	v_mul_f32_e32 v152, v37, v131
	v_lshl_add_u64 v[140:141], v[142:143], 0, v[138:139]
	v_lshl_add_u64 v[138:139], v[144:145], 0, v[138:139]
	s_nop 0
	v_mul_f32_e32 v133, v133, v206
	v_mul_f32_e32 v146, v146, v207
	v_mul_f32_e32 v147, v147, v208
	v_mul_f32_e32 v148, v148, v209
	v_mul_f32_e32 v149, v149, v206
	v_mul_f32_e32 v150, v150, v207
	v_cvt_pk_bf16_f32 v134, v133, v146
	v_cvt_pk_bf16_f32 v135, v147, v148
	v_mul_f32_e32 v136, v151, v208
	v_mul_f32_e32 v137, v152, v209
	global_store_dwordx2 v[140:141], v[134:135], off
	v_cvt_pk_bf16_f32 v134, v149, v150
	v_cvt_pk_bf16_f32 v135, v136, v137
	global_store_dwordx2 v[138:139], v[134:135], off
	s_nop 0
	v_mul_f32_e32 v138, v26, v130
	v_mul_f32_e32 v139, v27, v130
	v_mul_f32_e32 v140, v28, v130
	v_mul_f32_e32 v141, v29, v130
	v_add_u32_e32 v130, s2, v132
	v_mul_f32_e32 v146, v50, v131
	v_mul_f32_e32 v147, v51, v131
	v_mul_f32_e32 v148, v52, v131
	v_mul_f32_e32 v149, v53, v131
	v_ashrrev_i32_e32 v131, 31, v130
	v_lshlrev_b64 v[130:131], 14, v[130:131]
	v_lshl_add_u64 v[132:133], v[142:143], 0, v[130:131]
	v_lshl_add_u64 v[130:131], v[144:145], 0, v[130:131]
	s_nop 0
	v_mul_f32_e32 v138, v138, v210
	v_mul_f32_e32 v139, v139, v211
	v_mul_f32_e32 v140, v140, v212
	v_mul_f32_e32 v141, v141, v213
	v_mul_f32_e32 v142, v146, v210
	v_mul_f32_e32 v143, v147, v211
	v_mul_f32_e32 v136, v148, v212
	v_mul_f32_e32 v137, v149, v213
	v_cvt_pk_bf16_f32 v134, v138, v139
	v_cvt_pk_bf16_f32 v135, v140, v141
	global_store_dwordx2 v[132:133], v[134:135], off
	v_cvt_pk_bf16_f32 v132, v142, v143
	v_cvt_pk_bf16_f32 v133, v136, v137
	global_store_dwordx2 v[130:131], v[132:133], off

; #define GAS __attribute__((address_space(1)))
; __device__ __forceinline__ const float* x_row(const Args& A, int m) { return (m < MP) ? A.in[0] + (size_t)m * DM : A.in[1] + (size_t)(m - MP) * DM; }
; __device__ __forceinline__ void rms_pair_load(RPair& P, const Args& A, int m, int lane) {
;     if (m >= M) return;
;     const GAS f32x4* xr0 = (const GAS f32x4*)x_row(A, m) + lane; const GAS f32x4* xr1 = (const GAS f32x4*)x_row(A, m + 1) + lane;
; #pragma unroll
;     for (int j = 0; j < 4; ++j) { P.v0[j] = __builtin_nontemporal_load(xr0 + 64 * j); P.v1[j] = __builtin_nontemporal_load(xr1 + 64 * j); }
; }
; __device__ __forceinline__ void p0_prologue(Frame& F, const Args& A) {
;     ...
;     for (int m0 = 2 * gw; m0 < M; m0 += 10 * NGW) {
;         int ln = F.lane; asm volatile("" : "+v"(ln));
;         RPair pa, pb, pc, pd, pe; bf16* xn = (bf16*)(F.ws + WS_XN);
;         rms_pair_load(pa, A, m0, ln); rms_pair_load(pb, A, m0 + 2 * NGW, ln); rms_pair_load(pc, A, m0 + 4 * NGW, ln); rms_pair_load(pd, A, m0 + 6 * NGW, ln); rms_pair_load(pe, A, m0 + 8 * NGW, ln);
.LBB0_46:
	s_add_i32 s2, s62, 0xffffc000
	s_ashr_i32 s63, s62, 31
	s_cmpk_lt_i32 s62, 0x4000
	v_readlane_b32 s16, v251, 14
	s_cselect_b32 s3, s63, 0
	s_cselect_b32 s2, s62, s2
	v_readlane_b32 s17, v251, 15
	v_readlane_b32 s18, v251, 16
	v_readlane_b32 s19, v251, 17
	v_mov_b32_e32 v166, v200
	s_cselect_b32 s4, s17, s19
	s_cselect_b32 s5, s16, s18
	s_lshl_b64 s[2:3], s[2:3], 12
	s_add_u32 s2, s5, s2
	v_ashrrev_i32_e32 v167, 31, v166
	s_addc_u32 s3, s4, s3
	v_lshlrev_b64 v[164:165], 4, v[166:167]
	v_lshl_add_u64 v[130:131], s[2:3], 0, v[164:165]
	s_add_i32 s2, s62, 1
	s_add_i32 s4, s62, 0xffffc001
	s_ashr_i32 s3, s2, 31
	s_cmpk_lt_i32 s62, 0x3fff
	s_cselect_b32 s3, s3, 0
	s_cselect_b32 s2, s2, s4
	s_cselect_b32 s4, s17, s19
	s_cselect_b32 s5, s16, s18
	s_lshl_b64 s[2:3], s[2:3], 12
	s_add_u32 s2, s5, s2
	s_addc_u32 s3, s4, s3
	v_lshl_add_u64 v[132:133], s[2:3], 0, v[164:165]
	v_readlane_b32 s38, v251, 22
	v_readlane_b32 s39, v251, 23
	s_nop 3
	v_lshl_add_u64 v[214:215], v[166:167], 4, s[38:39]
	global_load_dwordx4 v[196:199], v[214:215], off
	global_load_dwordx4 v[202:205], v[214:215], off offset:1024
	global_load_dwordx4 v[206:209], v[214:215], off offset:2048
	global_load_dwordx4 v[210:213], v[214:215], off offset:3072
	global_load_dwordx4 v[158:161], v[130:131], off nt
	global_load_dwordx4 v[150:153], v[130:131], off offset:1024 nt
	global_load_dwordx4 v[154:157], v[132:133], off nt
	global_load_dwordx4 v[146:149], v[132:133], off offset:1024 nt
	global_load_dwordx4 v[142:145], v[130:131], off offset:2048 nt
	global_load_dwordx4 v[134:137], v[130:131], off offset:3072 nt
	global_load_dwordx4 v[138:141], v[132:133], off offset:2048 nt
	s_nop 0
	global_load_dwordx4 v[130:133], v[132:133], off offset:3072 nt
	s_add_i32 s34, s62, s0
	s_cmpk_lt_i32 s34, 0x4200
	s_cselect_b64 s[6:7], -1, 0
	s_cmpk_gt_i32 s34, 0x41ff
	v_readlane_b32 s20, v251, 18
	v_readlane_b32 s21, v251, 19
	v_readlane_b32 s22, v251, 20
	v_readlane_b32 s23, v251, 21
	v_readlane_b32 s24, v251, 22
	v_readlane_b32 s25, v251, 23
	v_readlane_b32 s26, v251, 24
	v_readlane_b32 s27, v251, 25
	v_readlane_b32 s28, v251, 26
	v_readlane_b32 s29, v251, 27
	v_readlane_b32 s30, v251, 28
	v_readlane_b32 s31, v251, 29
	s_cbranch_scc1 .LBB0_48
	s_add_i32 s2, s34, 0xffffc000
	s_ashr_i32 s3, s34, 31
	s_cmpk_lt_i32 s34, 0x4000
	v_readlane_b32 s16, v251, 14
	s_cselect_b32 s3, s3, 0
	s_cselect_b32 s2, s34, s2
	v_readlane_b32 s17, v251, 15
	v_readlane_b32 s18, v251, 16
	v_readlane_b32 s19, v251, 17
	s_cselect_b32 s4, s17, s19
	s_cselect_b32 s5, s16, s18
	s_lshl_b64 s[2:3], s[2:3], 12
	s_add_u32 s2, s5, s2
	s_addc_u32 s3, s4, s3
	v_lshl_add_u64 v[118:119], s[2:3], 0, v[164:165]
	s_add_i32 s2, s34, 1
	s_add_i32 s4, s34, 0xffffc001
	s_ashr_i32 s3, s2, 31
	s_cmpk_lt_i32 s34, 0x3fff
	s_cselect_b32 s3, s3, 0
	s_cselect_b32 s2, s2, s4
	s_cselect_b32 s4, s17, s19
	s_cselect_b32 s5, s16, s18
	s_lshl_b64 s[2:3], s[2:3], 12
	s_add_u32 s2, s5, s2
	s_addc_u32 s3, s4, s3
	v_lshl_add_u64 v[126:127], s[2:3], 0, v[164:165]
	global_load_dwordx4 v[78:81], v[118:119], off nt
	global_load_dwordx4 v[94:97], v[118:119], off offset:1024 nt
	global_load_dwordx4 v[106:109], v[126:127], off nt
	global_load_dwordx4 v[114:117], v[126:127], off offset:1024 nt
	global_load_dwordx4 v[102:105], v[118:119], off offset:2048 nt
	s_nop 0
	global_load_dwordx4 v[118:121], v[118:119], off offset:3072 nt
	s_nop 0
	global_load_dwordx4 v[122:125], v[126:127], off offset:2048 nt
	s_nop 0
	global_load_dwordx4 v[126:129], v[126:127], off offset:3072 nt
	v_readlane_b32 s20, v251, 18
	v_readlane_b32 s21, v251, 19
	v_readlane_b32 s22, v251, 20
	v_readlane_b32 s23, v251, 21
	v_readlane_b32 s24, v251, 22
	v_readlane_b32 s25, v251, 23
	v_readlane_b32 s26, v251, 24
	v_readlane_b32 s27, v251, 25
	v_readlane_b32 s28, v251, 26
	v_readlane_b32 s29, v251, 27
	v_readlane_b32 s30, v251, 28
	v_readlane_b32 s31, v251, 29

; __host__ __device__ __forceinline__ size_t img_off(int row, int col, int nkt) { return ((size_t)((row >> 7) * nkt + (col >> 6)) << 14) + (size_t)lds_byte(row & 127, col & 63); }
; #define GAS __attribute__((address_space(1)))
; __device__ __forceinline__ unsigned pk2(float lo, float hi) { return pg8::cvt_pk_bf16(lo, hi); }
; __device__ __forceinline__ void rms_pair_finish(const RPair& P, const float* g, bf16* obase, float* rs, int m, int lane) {
;     if (m >= M) return;
;     const GAS f32x4* gr = (const GAS f32x4*)g + lane; float s0 = 0.f, s1 = 0.f;
; #pragma unroll
;     for (int j = 0; j < 4; ++j) { s0 += (P.v0[j].x * P.v0[j].x + P.v0[j].y * P.v0[j].y) + (P.v0[j].z * P.v0[j].z + P.v0[j].w * P.v0[j].w); s1 += (P.v1[j].x * P.v1[j].x + P.v1[j].y * P.v1[j].y) + (P.v1[j].z * P.v1[j].z + P.v1[j].w * P.v1[j].w); }
;     const float r0 = 1.f / sqrtf(wave_sum(s0) * (1.f / DM) + EPS), r1 = 1.f / sqrtf(wave_sum(s1) * (1.f / DM) + EPS);
;     if (lane == 0) { rs[m] = r0; rs[m + 1] = r1; }
; #pragma unroll
;     for (int j = 0; j < 4; ++j) { const f32x4 gg = gr[64 * j]; v2u o;
;         o.x = pk2(P.v0[j].x * r0 * gg.x, P.v0[j].y * r0 * gg.y); o.y = pk2(P.v0[j].z * r0 * gg.z, P.v0[j].w * r0 * gg.w); *(GAS v2u*)((GAS char*)obase + pg8::img_off(m, 4 * lane + 256 * j, DM / 64)) = o;
;         o.x = pk2(P.v1[j].x * r1 * gg.x, P.v1[j].y * r1 * gg.y); o.y = pk2(P.v1[j].z * r1 * gg.z, P.v1[j].w * r1 * gg.w); *(GAS v2u*)((GAS char*)obase + pg8::img_off(m + 1, 4 * lane + 256 * j, DM / 64)) = o; }
.LBB0_56:
	s_or_b64 exec, exec, s[4:5]
	v_readlane_b32 s16, v251, 14
	v_readlane_b32 s24, v251, 22
	v_readlane_b32 s25, v251, 23
	v_lshlrev_b32_e32 v186, 2, v166
	v_mul_f32_e32 v190, v154, v169
	v_lshl_add_u64 v[164:165], v[166:167], 4, s[24:25]
	s_nop 0
	v_and_b32_e32 v154, 60, v186
	s_lshr_b32 s5, s62, 3
	v_mul_f32_e32 v191, v155, v169
	v_bfe_u32 v155, v186, 5, 1
	v_lshlrev_b32_e32 v154, 1, v154
	s_ashr_i32 s4, s62, 3
	s_and_b32 s35, s11, 0x380
	s_lshr_b32 s36, s11, 4
	v_mul_f32_e32 v189, v161, v168
	v_mul_f32_e32 v192, v156, v169
	v_and_or_b32 v161, s5, 14, v155
	v_and_b32_e32 v156, 56, v154
	v_mul_f32_e32 v187, v158, v168
	v_ashrrev_i32_e32 v158, 4, v166
	s_and_b32 s4, s4, -16
	s_and_b32 s36, s36, 32
	v_lshlrev_b32_e32 v182, 10, v161
	v_or_b32_e32 v162, s35, v156
	v_mul_f32_e32 v188, v160, v168
	v_add_u32_e32 v160, s4, v158
	v_or3_b32 v183, v154, s35, 64
	v_bitop3_b32 v162, v162, v182, s36 bitop3:0xde
	v_ashrrev_i32_e32 v161, 31, v160
	v_lshl_add_u64 v[166:167], s[14:15], 0, v[162:163]
	v_bitop3_b32 v162, v183, v182, s36 bitop3:0xde
	v_mul_f32_e32 v159, v159, v168
	v_lshlrev_b64 v[160:161], 14, v[160:161]
	v_lshl_add_u64 v[182:183], s[14:15], 0, v[162:163]
	v_mul_f32_e32 v157, v157, v169
	v_lshl_add_u64 v[184:185], v[166:167], 0, v[160:161]
	v_lshl_add_u64 v[160:161], v[182:183], 0, v[160:161]
	v_mul_f32_e32 v153, v153, v168
	v_mul_f32_e32 v152, v152, v168
	v_mul_f32_e32 v147, v147, v169
	v_mul_f32_e32 v145, v145, v168
	v_mul_f32_e32 v144, v144, v168
	v_mul_f32_e32 v139, v139, v169
	v_mul_f32_e32 v137, v137, v168
	v_mul_f32_e32 v136, v136, v168
	v_mul_f32_e32 v133, v133, v169
	s_andn2_b64 vcc, exec, s[6:7]
	v_readlane_b32 s17, v251, 15
	v_readlane_b32 s18, v251, 16
	v_readlane_b32 s19, v251, 17
	v_readlane_b32 s20, v251, 18
	v_readlane_b32 s21, v251, 19
	v_readlane_b32 s22, v251, 20
	v_readlane_b32 s23, v251, 21
	v_readlane_b32 s26, v251, 24
	v_readlane_b32 s27, v251, 25
	v_readlane_b32 s28, v251, 26
	v_readlane_b32 s29, v251, 27
	v_readlane_b32 s30, v251, 28
	v_readlane_b32 s31, v251, 29
	s_waitcnt vmcnt(8)
	v_mul_f32_e32 v162, v187, v196
	v_mul_f32_e32 v159, v159, v197
	v_mul_f32_e32 v187, v188, v198
	v_mul_f32_e32 v188, v189, v199
	v_mul_f32_e32 v189, v190, v196
	v_mul_f32_e32 v190, v191, v197
	v_cvt_pk_bf16_f32 v178, v162, v159
	v_cvt_pk_bf16_f32 v179, v187, v188
	v_mul_f32_e32 v180, v192, v198
	v_mul_f32_e32 v157, v157, v199
	global_store_dwordx2 v[184:185], v[178:179], off
	v_cvt_pk_bf16_f32 v178, v189, v190
	v_cvt_pk_bf16_f32 v179, v180, v157
	global_store_dwordx2 v[160:161], v[178:179], off
	s_nop 0
	v_mul_f32_e32 v160, v146, v169
	v_add_u32_e32 v146, 0x100, v186
	v_ashrrev_i32_e32 v146, 6, v146
	v_mul_f32_e32 v161, v148, v169
	v_add_u32_e32 v148, s4, v146
	v_mul_f32_e32 v162, v149, v169
	v_ashrrev_i32_e32 v149, 31, v148
	v_lshlrev_b64 v[148:149], 14, v[148:149]
	v_mul_f32_e32 v157, v150, v168
	v_mul_f32_e32 v159, v151, v168
	v_lshl_add_u64 v[150:151], v[166:167], 0, v[148:149]
	v_lshl_add_u64 v[148:149], v[182:183], 0, v[148:149]
	s_nop 0
	v_mul_f32_e32 v153, v153, v205
	v_mul_f32_e32 v157, v157, v202
	v_mul_f32_e32 v159, v159, v203
	v_mul_f32_e32 v184, v152, v204
	v_mul_f32_e32 v160, v160, v202
	v_mul_f32_e32 v147, v147, v203
	v_mul_f32_e32 v161, v161, v204
	v_mul_f32_e32 v162, v162, v205
	v_cvt_pk_bf16_f32 v152, v157, v159
	v_cvt_pk_bf16_f32 v153, v184, v153
	global_store_dwordx2 v[150:151], v[152:153], off
	v_cvt_pk_bf16_f32 v150, v160, v147
	v_cvt_pk_bf16_f32 v151, v161, v162
	global_store_dwordx2 v[148:149], v[150:151], off
	s_nop 0
	v_mul_f32_e32 v153, v138, v169
	v_add_u32_e32 v138, 0x200, v186
	v_ashrrev_i32_e32 v138, 6, v138
	v_mul_f32_e32 v157, v140, v169
	v_add_u32_e32 v140, s4, v138
	v_mul_f32_e32 v159, v141, v169
	v_ashrrev_i32_e32 v141, 31, v140
	v_lshlrev_b64 v[140:141], 14, v[140:141]
	v_mul_f32_e32 v147, v142, v168
	v_mul_f32_e32 v152, v143, v168
	v_lshl_add_u64 v[142:143], v[166:167], 0, v[140:141]
	v_lshl_add_u64 v[140:141], v[182:183], 0, v[140:141]
	s_nop 0
	v_mul_f32_e32 v145, v145, v209
	v_mul_f32_e32 v147, v147, v206
	v_mul_f32_e32 v152, v152, v207
	v_mul_f32_e32 v160, v144, v208
	v_mul_f32_e32 v148, v153, v206
	v_mul_f32_e32 v139, v139, v207
	v_mul_f32_e32 v149, v157, v208
	v_mul_f32_e32 v150, v159, v209
	v_cvt_pk_bf16_f32 v144, v147, v152
	v_cvt_pk_bf16_f32 v145, v160, v145
	global_store_dwordx2 v[142:143], v[144:145], off
	v_cvt_pk_bf16_f32 v142, v148, v139
	v_cvt_pk_bf16_f32 v143, v149, v150
	global_store_dwordx2 v[140:141], v[142:143], off
	s_nop 0
	v_mul_f32_e32 v145, v130, v169
	v_add_u32_e32 v130, 0x300, v186
	v_mul_f32_e32 v148, v132, v169
	v_ashrrev_i32_e32 v132, 6, v130
	v_add_u32_e32 v130, s4, v132
	v_mul_f32_e32 v147, v131, v169
	v_ashrrev_i32_e32 v131, 31, v130
	v_lshlrev_b64 v[130:131], 14, v[130:131]
	v_mul_f32_e32 v139, v134, v168
	v_mul_f32_e32 v144, v135, v168
	v_lshl_add_u64 v[134:135], v[166:167], 0, v[130:131]
	v_lshl_add_u64 v[130:131], v[182:183], 0, v[130:131]
	s_nop 0
	v_mul_f32_e32 v137, v137, v213
	v_mul_f32_e32 v139, v139, v210
	v_mul_f32_e32 v144, v144, v211
	v_mul_f32_e32 v149, v136, v212
	v_mul_f32_e32 v140, v145, v210
	v_mul_f32_e32 v141, v147, v211
	v_mul_f32_e32 v142, v148, v212
	v_mul_f32_e32 v133, v133, v213
	v_cvt_pk_bf16_f32 v136, v139, v144
	v_cvt_pk_bf16_f32 v137, v149, v137
	global_store_dwordx2 v[134:135], v[136:137], off
	v_cvt_pk_bf16_f32 v134, v140, v141
	v_cvt_pk_bf16_f32 v135, v142, v133
	global_store_dwordx2 v[130:131], v[134:135], off
	s_cbranch_vccz .LBB0_60
	s_andn2_b64 vcc, exec, s[60:61]
	s_cbranch_vccz .LBB0_63

; __host__ __device__ __forceinline__ size_t img_off(int row, int col, int nkt) { return ((size_t)((row >> 7) * nkt + (col >> 6)) << 14) + (size_t)lds_byte(row & 127, col & 63); }
; #define GAS __attribute__((address_space(1)))
; __device__ __forceinline__ unsigned pk2(float lo, float hi) { return pg8::cvt_pk_bf16(lo, hi); }
; __device__ __forceinline__ void rms_pair_finish(const RPair& P, const float* g, bf16* obase, float* rs, int m, int lane) {
;     if (m >= M) return;
;     const GAS f32x4* gr = (const GAS f32x4*)g + lane; float s0 = 0.f, s1 = 0.f;
; #pragma unroll
;     for (int j = 0; j < 4; ++j) { s0 += (P.v0[j].x * P.v0[j].x + P.v0[j].y * P.v0[j].y) + (P.v0[j].z * P.v0[j].z + P.v0[j].w * P.v0[j].w); s1 += (P.v1[j].x * P.v1[j].x + P.v1[j].y * P.v1[j].y) + (P.v1[j].z * P.v1[j].z + P.v1[j].w * P.v1[j].w); }
;     const float r0 = 1.f / sqrtf(wave_sum(s0) * (1.f / DM) + EPS), r1 = 1.f / sqrtf(wave_sum(s1) * (1.f / DM) + EPS);
;     if (lane == 0) { rs[m] = r0; rs[m + 1] = r1; }
; #pragma unroll
;     for (int j = 0; j < 4; ++j) { const f32x4 gg = gr[64 * j]; v2u o;
;         o.x = pk2(P.v0[j].x * r0 * gg.x, P.v0[j].y * r0 * gg.y); o.y = pk2(P.v0[j].z * r0 * gg.z, P.v0[j].w * r0 * gg.w); *(GAS v2u*)((GAS char*)obase + pg8::img_off(m, 4 * lane + 256 * j, DM / 64)) = o;
;         o.x = pk2(P.v1[j].x * r1 * gg.x, P.v1[j].y * r1 * gg.y); o.y = pk2(P.v1[j].z * r1 * gg.z, P.v1[j].w * r1 * gg.w); *(GAS v2u*)((GAS char*)obase + pg8::img_off(m + 1, 4 * lane + 256 * j, DM / 64)) = o; }
.LBB0_62:
	s_or_b64 exec, exec, s[4:5]
	s_nop 0
	s_lshr_b32 s5, s34, 3
	s_add_i32 s6, s70, s11
	s_ashr_i32 s4, s34, 3
	v_and_or_b32 v140, s5, 14, v155
	s_and_b32 s5, s6, 0x380
	s_lshr_b32 s6, s6, 4
	s_and_b32 s4, s4, -16
	v_or_b32_e32 v141, s5, v156
	v_lshlrev_b32_e32 v144, 10, v140
	s_and_b32 s6, s6, 32
	v_or3_b32 v145, s5, v154, 64
	v_add_u32_e32 v140, s4, v158
	v_bitop3_b32 v162, v141, v144, s6 bitop3:0xde
	v_ashrrev_i32_e32 v141, 31, v140
	v_lshl_add_u64 v[142:143], s[14:15], 0, v[162:163]
	v_bitop3_b32 v162, v145, v144, s6 bitop3:0xde
	v_mul_f32_e32 v133, v78, v130
	v_mul_f32_e32 v139, v79, v130
	v_mul_f32_e32 v147, v80, v130
	v_mul_f32_e32 v150, v81, v130
	v_mul_f32_e32 v151, v106, v131
	v_mul_f32_e32 v152, v107, v131
	v_lshlrev_b64 v[140:141], 14, v[140:141]
	v_lshl_add_u64 v[144:145], s[14:15], 0, v[162:163]
	v_mul_f32_e32 v153, v108, v131
	v_mul_f32_e32 v157, v109, v131
	v_lshl_add_u64 v[148:149], v[142:143], 0, v[140:141]
	v_lshl_add_u64 v[140:141], v[144:145], 0, v[140:141]
	s_waitcnt vmcnt(8)
	v_mul_f32_e32 v133, v133, v196
	v_mul_f32_e32 v139, v139, v197
	v_mul_f32_e32 v147, v147, v198
	v_mul_f32_e32 v150, v150, v199
	v_mul_f32_e32 v151, v151, v196
	v_mul_f32_e32 v152, v152, v197
	v_cvt_pk_bf16_f32 v134, v133, v139
	v_cvt_pk_bf16_f32 v135, v147, v150
	v_mul_f32_e32 v136, v153, v198
	v_mul_f32_e32 v137, v157, v199
	global_store_dwordx2 v[148:149], v[134:135], off
	v_cvt_pk_bf16_f32 v134, v151, v152
	v_cvt_pk_bf16_f32 v135, v136, v137
	global_store_dwordx2 v[140:141], v[134:135], off
	s_nop 0
	v_add_u32_e32 v140, s4, v146
	v_ashrrev_i32_e32 v141, 31, v140
	v_mul_f32_e32 v133, v94, v130
	v_mul_f32_e32 v139, v95, v130
	v_mul_f32_e32 v147, v96, v130
	v_mul_f32_e32 v150, v97, v130
	v_mul_f32_e32 v151, v114, v131
	v_mul_f32_e32 v152, v115, v131
	v_lshlrev_b64 v[140:141], 14, v[140:141]
	v_mul_f32_e32 v153, v116, v131
	v_mul_f32_e32 v157, v117, v131
	v_lshl_add_u64 v[148:149], v[142:143], 0, v[140:141]
	v_lshl_add_u64 v[140:141], v[144:145], 0, v[140:141]
	s_nop 0
	v_mul_f32_e32 v133, v133, v202
	v_mul_f32_e32 v139, v139, v203
	v_mul_f32_e32 v147, v147, v204
	v_mul_f32_e32 v150, v150, v205
	v_mul_f32_e32 v151, v151, v202
	v_mul_f32_e32 v152, v152, v203
	v_cvt_pk_bf16_f32 v134, v133, v139
	v_cvt_pk_bf16_f32 v135, v147, v150
	v_mul_f32_e32 v136, v153, v204
	v_mul_f32_e32 v137, v157, v205
	global_store_dwordx2 v[148:149], v[134:135], off
	v_cvt_pk_bf16_f32 v134, v151, v152
	v_cvt_pk_bf16_f32 v135, v136, v137
	global_store_dwordx2 v[140:141], v[134:135], off
	s_nop 0
	v_add_u32_e32 v140, s4, v138
	v_ashrrev_i32_e32 v141, 31, v140
	v_mul_f32_e32 v133, v102, v130
	v_mul_f32_e32 v139, v103, v130
	v_mul_f32_e32 v147, v104, v130
	v_mul_f32_e32 v150, v105, v130
	v_mul_f32_e32 v151, v122, v131
	v_mul_f32_e32 v152, v123, v131
	v_lshlrev_b64 v[140:141], 14, v[140:141]
	v_mul_f32_e32 v153, v124, v131
	v_mul_f32_e32 v157, v125, v131
	v_lshl_add_u64 v[148:149], v[142:143], 0, v[140:141]
	v_lshl_add_u64 v[140:141], v[144:145], 0, v[140:141]
	s_nop 0
	v_mul_f32_e32 v133, v133, v206
	v_mul_f32_e32 v139, v139, v207
	v_mul_f32_e32 v147, v147, v208
	v_mul_f32_e32 v150, v150, v209
	v_mul_f32_e32 v151, v151, v206
	v_mul_f32_e32 v152, v152, v207
	v_cvt_pk_bf16_f32 v134, v133, v139
	v_cvt_pk_bf16_f32 v135, v147, v150
	v_mul_f32_e32 v136, v153, v208
	v_mul_f32_e32 v137, v157, v209
	global_store_dwordx2 v[148:149], v[134:135], off
	v_cvt_pk_bf16_f32 v134, v151, v152
	v_cvt_pk_bf16_f32 v135, v136, v137
	global_store_dwordx2 v[140:141], v[134:135], off
	s_nop 0
	v_mul_f32_e32 v133, v118, v130
	v_mul_f32_e32 v139, v119, v130
	v_mul_f32_e32 v147, v120, v130
	v_mul_f32_e32 v148, v121, v130
	v_add_u32_e32 v130, s4, v132
	v_mul_f32_e32 v149, v126, v131
	v_mul_f32_e32 v150, v127, v131
	v_mul_f32_e32 v151, v128, v131
	v_mul_f32_e32 v152, v129, v131
	v_ashrrev_i32_e32 v131, 31, v130
	v_lshlrev_b64 v[130:131], 14, v[130:131]
	v_lshl_add_u64 v[140:141], v[142:143], 0, v[130:131]
	v_lshl_add_u64 v[130:131], v[144:145], 0, v[130:131]
	s_nop 0
	v_mul_f32_e32 v133, v133, v210
	v_mul_f32_e32 v139, v139, v211
	v_mul_f32_e32 v142, v147, v212
	v_mul_f32_e32 v143, v148, v213
	v_mul_f32_e32 v147, v149, v210
	v_mul_f32_e32 v148, v150, v211
	v_cvt_pk_bf16_f32 v134, v133, v139
	v_cvt_pk_bf16_f32 v135, v142, v143
	v_mul_f32_e32 v136, v151, v212
	v_mul_f32_e32 v137, v152, v213
	global_store_dwordx2 v[140:141], v[134:135], off
	v_cvt_pk_bf16_f32 v134, v147, v148
	v_cvt_pk_bf16_f32 v135, v136, v137
	global_store_dwordx2 v[130:131], v[134:135], off
	s_andn2_b64 vcc, exec, s[60:61]
	s_cbranch_vccnz .LBB0_58

; __host__ __device__ __forceinline__ size_t img_off(int row, int col, int nkt) { return ((size_t)((row >> 7) * nkt + (col >> 6)) << 14) + (size_t)lds_byte(row & 127, col & 63); }
; #define GAS __attribute__((address_space(1)))
; __device__ __forceinline__ unsigned pk2(float lo, float hi) { return pg8::cvt_pk_bf16(lo, hi); }
; __device__ __forceinline__ void rms_pair_finish(const RPair& P, const float* g, bf16* obase, float* rs, int m, int lane) {
;     if (m >= M) return;
;     const GAS f32x4* gr = (const GAS f32x4*)g + lane; float s0 = 0.f, s1 = 0.f;
; #pragma unroll
;     for (int j = 0; j < 4; ++j) { s0 += (P.v0[j].x * P.v0[j].x + P.v0[j].y * P.v0[j].y) + (P.v0[j].z * P.v0[j].z + P.v0[j].w * P.v0[j].w); s1 += (P.v1[j].x * P.v1[j].x + P.v1[j].y * P.v1[j].y) + (P.v1[j].z * P.v1[j].z + P.v1[j].w * P.v1[j].w); }
;     const float r0 = 1.f / sqrtf(wave_sum(s0) * (1.f / DM) + EPS), r1 = 1.f / sqrtf(wave_sum(s1) * (1.f / DM) + EPS);
;     if (lane == 0) { rs[m] = r0; rs[m + 1] = r1; }
; #pragma unroll
;     for (int j = 0; j < 4; ++j) { const f32x4 gg = gr[64 * j]; v2u o;
;         o.x = pk2(P.v0[j].x * r0 * gg.x, P.v0[j].y * r0 * gg.y); o.y = pk2(P.v0[j].z * r0 * gg.z, P.v0[j].w * r0 * gg.w); *(GAS v2u*)((GAS char*)obase + pg8::img_off(m, 4 * lane + 256 * j, DM / 64)) = o;
;         o.x = pk2(P.v1[j].x * r1 * gg.x, P.v1[j].y * r1 * gg.y); o.y = pk2(P.v1[j].z * r1 * gg.z, P.v1[j].w * r1 * gg.w); *(GAS v2u*)((GAS char*)obase + pg8::img_off(m + 1, 4 * lane + 256 * j, DM / 64)) = o; }
.LBB0_65:
	s_or_b64 exec, exec, s[4:5]
	s_nop 0
	s_lshr_b32 s5, s58, 3
	s_add_i32 s6, s65, s11
	s_ashr_i32 s4, s58, 3
	v_and_or_b32 v140, s5, 14, v155
	s_and_b32 s5, s6, 0x380
	s_lshr_b32 s6, s6, 4
	s_and_b32 s4, s4, -16
	v_or_b32_e32 v141, s5, v156
	v_lshlrev_b32_e32 v144, 10, v140
	s_and_b32 s6, s6, 32
	v_or3_b32 v145, s5, v154, 64
	v_add_u32_e32 v140, s4, v158
	v_bitop3_b32 v162, v141, v144, s6 bitop3:0xde
	v_ashrrev_i32_e32 v141, 31, v140
	v_lshl_add_u64 v[142:143], s[14:15], 0, v[162:163]
	v_bitop3_b32 v162, v145, v144, s6 bitop3:0xde
	v_mul_f32_e32 v133, v46, v130
	v_mul_f32_e32 v139, v47, v130
	v_mul_f32_e32 v147, v48, v130
	v_mul_f32_e32 v150, v49, v130
	v_mul_f32_e32 v151, v70, v131
	v_mul_f32_e32 v152, v71, v131
	v_lshlrev_b64 v[140:141], 14, v[140:141]
	v_lshl_add_u64 v[144:145], s[14:15], 0, v[162:163]
	v_mul_f32_e32 v153, v72, v131
	v_mul_f32_e32 v157, v73, v131
	v_lshl_add_u64 v[148:149], v[142:143], 0, v[140:141]
	v_lshl_add_u64 v[140:141], v[144:145], 0, v[140:141]
	s_waitcnt vmcnt(8)
	v_mul_f32_e32 v133, v133, v196
	v_mul_f32_e32 v139, v139, v197
	v_mul_f32_e32 v147, v147, v198
	v_mul_f32_e32 v150, v150, v199
	v_mul_f32_e32 v151, v151, v196
	v_mul_f32_e32 v152, v152, v197
	v_cvt_pk_bf16_f32 v134, v133, v139
	v_cvt_pk_bf16_f32 v135, v147, v150
	v_mul_f32_e32 v136, v153, v198
	v_mul_f32_e32 v137, v157, v199
	global_store_dwordx2 v[148:149], v[134:135], off
	v_cvt_pk_bf16_f32 v134, v151, v152
	v_cvt_pk_bf16_f32 v135, v136, v137
	global_store_dwordx2 v[140:141], v[134:135], off
	s_nop 0
	v_add_u32_e32 v140, s4, v146
	v_ashrrev_i32_e32 v141, 31, v140
	v_mul_f32_e32 v133, v62, v130
	v_mul_f32_e32 v139, v63, v130
	v_mul_f32_e32 v147, v64, v130
	v_mul_f32_e32 v150, v65, v130
	v_mul_f32_e32 v151, v86, v131
	v_mul_f32_e32 v152, v87, v131
	v_lshlrev_b64 v[140:141], 14, v[140:141]
	v_mul_f32_e32 v153, v88, v131
	v_mul_f32_e32 v157, v89, v131
	v_lshl_add_u64 v[148:149], v[142:143], 0, v[140:141]
	v_lshl_add_u64 v[140:141], v[144:145], 0, v[140:141]
	s_nop 0
	v_mul_f32_e32 v133, v133, v202
	v_mul_f32_e32 v139, v139, v203
	v_mul_f32_e32 v147, v147, v204
	v_mul_f32_e32 v150, v150, v205
	v_mul_f32_e32 v151, v151, v202
	v_mul_f32_e32 v152, v152, v203
	v_cvt_pk_bf16_f32 v134, v133, v139
	v_cvt_pk_bf16_f32 v135, v147, v150
	v_mul_f32_e32 v136, v153, v204
	v_mul_f32_e32 v137, v157, v205
	global_store_dwordx2 v[148:149], v[134:135], off
	v_cvt_pk_bf16_f32 v134, v151, v152
	v_cvt_pk_bf16_f32 v135, v136, v137
	global_store_dwordx2 v[140:141], v[134:135], off
	s_nop 0
	v_add_u32_e32 v140, s4, v138
	v_ashrrev_i32_e32 v141, 31, v140
	v_mul_f32_e32 v133, v74, v130
	v_mul_f32_e32 v139, v75, v130
	v_mul_f32_e32 v147, v76, v130
	v_mul_f32_e32 v150, v77, v130
	v_mul_f32_e32 v151, v98, v131
	v_mul_f32_e32 v152, v99, v131
	v_lshlrev_b64 v[140:141], 14, v[140:141]
	v_mul_f32_e32 v153, v100, v131
	v_mul_f32_e32 v157, v101, v131
	v_lshl_add_u64 v[148:149], v[142:143], 0, v[140:141]
	v_lshl_add_u64 v[140:141], v[144:145], 0, v[140:141]
	s_nop 0
	v_mul_f32_e32 v133, v133, v206
	v_mul_f32_e32 v139, v139, v207
	v_mul_f32_e32 v147, v147, v208
	v_mul_f32_e32 v150, v150, v209
	v_mul_f32_e32 v151, v151, v206
	v_mul_f32_e32 v152, v152, v207
	v_cvt_pk_bf16_f32 v134, v133, v139
	v_cvt_pk_bf16_f32 v135, v147, v150
	v_mul_f32_e32 v136, v153, v208
	v_mul_f32_e32 v137, v157, v209
	global_store_dwordx2 v[148:149], v[134:135], off
	v_cvt_pk_bf16_f32 v134, v151, v152
	v_cvt_pk_bf16_f32 v135, v136, v137
	global_store_dwordx2 v[140:141], v[134:135], off
	s_nop 0
	v_mul_f32_e32 v133, v90, v130
	v_mul_f32_e32 v139, v91, v130
	v_mul_f32_e32 v147, v92, v130
	v_mul_f32_e32 v148, v93, v130
	v_add_u32_e32 v130, s4, v132
	v_mul_f32_e32 v149, v110, v131
	v_mul_f32_e32 v150, v111, v131
	v_mul_f32_e32 v151, v112, v131
	v_mul_f32_e32 v152, v113, v131
	v_ashrrev_i32_e32 v131, 31, v130
	v_lshlrev_b64 v[130:131], 14, v[130:131]
	v_lshl_add_u64 v[140:141], v[142:143], 0, v[130:131]
	v_lshl_add_u64 v[130:131], v[144:145], 0, v[130:131]
	s_nop 0
	v_mul_f32_e32 v133, v133, v210
	v_mul_f32_e32 v139, v139, v211
	v_mul_f32_e32 v142, v147, v212
	v_mul_f32_e32 v143, v148, v213
	v_mul_f32_e32 v147, v149, v210
	v_mul_f32_e32 v148, v150, v211
	v_cvt_pk_bf16_f32 v134, v133, v139
	v_cvt_pk_bf16_f32 v135, v142, v143
	v_mul_f32_e32 v136, v151, v212
	v_mul_f32_e32 v137, v152, v213
	global_store_dwordx2 v[140:141], v[134:135], off
	v_cvt_pk_bf16_f32 v134, v147, v148
	v_cvt_pk_bf16_f32 v135, v136, v137
	global_store_dwordx2 v[130:131], v[134:135], off
	s_andn2_b64 vcc, exec, s[12:13]
	s_cbranch_vccnz .LBB0_59

; __host__ __device__ __forceinline__ size_t img_off(int row, int col, int nkt) { return ((size_t)((row >> 7) * nkt + (col >> 6)) << 14) + (size_t)lds_byte(row & 127, col & 63); }
; #define GAS __attribute__((address_space(1)))
; __device__ __forceinline__ unsigned pk2(float lo, float hi) { return pg8::cvt_pk_bf16(lo, hi); }
; __device__ __forceinline__ void rms_pair_finish(const RPair& P, const float* g, bf16* obase, float* rs, int m, int lane) {
;     if (m >= M) return;
;     const GAS f32x4* gr = (const GAS f32x4*)g + lane; float s0 = 0.f, s1 = 0.f;
; #pragma unroll
;     for (int j = 0; j < 4; ++j) { s0 += (P.v0[j].x * P.v0[j].x + P.v0[j].y * P.v0[j].y) + (P.v0[j].z * P.v0[j].z + P.v0[j].w * P.v0[j].w); s1 += (P.v1[j].x * P.v1[j].x + P.v1[j].y * P.v1[j].y) + (P.v1[j].z * P.v1[j].z + P.v1[j].w * P.v1[j].w); }
;     const float r0 = 1.f / sqrtf(wave_sum(s0) * (1.f / DM) + EPS), r1 = 1.f / sqrtf(wave_sum(s1) * (1.f / DM) + EPS);
;     if (lane == 0) { rs[m] = r0; rs[m + 1] = r1; }
; #pragma unroll
;     for (int j = 0; j < 4; ++j) { const f32x4 gg = gr[64 * j]; v2u o;
;         o.x = pk2(P.v0[j].x * r0 * gg.x, P.v0[j].y * r0 * gg.y); o.y = pk2(P.v0[j].z * r0 * gg.z, P.v0[j].w * r0 * gg.w); *(GAS v2u*)((GAS char*)obase + pg8::img_off(m, 4 * lane + 256 * j, DM / 64)) = o;
;         o.x = pk2(P.v1[j].x * r1 * gg.x, P.v1[j].y * r1 * gg.y); o.y = pk2(P.v1[j].z * r1 * gg.z, P.v1[j].w * r1 * gg.w); *(GAS v2u*)((GAS char*)obase + pg8::img_off(m + 1, 4 * lane + 256 * j, DM / 64)) = o; }
.LBB0_68:
	s_or_b64 exec, exec, s[4:5]
	s_nop 0
	s_lshr_b32 s5, s56, 3
	s_add_i32 s6, s67, s11
	s_ashr_i32 s4, s56, 3
	v_and_or_b32 v140, s5, 14, v155
	s_and_b32 s5, s6, 0x380
	s_lshr_b32 s6, s6, 4
	s_and_b32 s4, s4, -16
	v_or_b32_e32 v141, s5, v156
	v_lshlrev_b32_e32 v144, 10, v140
	s_and_b32 s6, s6, 32
	v_or3_b32 v145, s5, v154, 64
	v_add_u32_e32 v140, s4, v158
	v_bitop3_b32 v162, v141, v144, s6 bitop3:0xde
	v_ashrrev_i32_e32 v141, 31, v140
	v_lshl_add_u64 v[142:143], s[14:15], 0, v[162:163]
	v_bitop3_b32 v162, v145, v144, s6 bitop3:0xde
	v_mul_f32_e32 v133, v18, v130
	v_mul_f32_e32 v139, v19, v130
	v_mul_f32_e32 v147, v20, v130
	v_mul_f32_e32 v150, v21, v130
	v_mul_f32_e32 v151, v38, v131
	v_mul_f32_e32 v152, v39, v131
	v_lshlrev_b64 v[140:141], 14, v[140:141]
	v_lshl_add_u64 v[144:145], s[14:15], 0, v[162:163]
	v_mul_f32_e32 v153, v40, v131
	v_mul_f32_e32 v157, v41, v131
	v_lshl_add_u64 v[148:149], v[142:143], 0, v[140:141]
	v_lshl_add_u64 v[140:141], v[144:145], 0, v[140:141]
	s_waitcnt vmcnt(8)
	v_mul_f32_e32 v133, v133, v196
	v_mul_f32_e32 v139, v139, v197
	v_mul_f32_e32 v147, v147, v198
	v_mul_f32_e32 v150, v150, v199
	v_mul_f32_e32 v151, v151, v196
	v_mul_f32_e32 v152, v152, v197
	v_cvt_pk_bf16_f32 v134, v133, v139
	v_cvt_pk_bf16_f32 v135, v147, v150
	v_mul_f32_e32 v136, v153, v198
	v_mul_f32_e32 v137, v157, v199
	global_store_dwordx2 v[148:149], v[134:135], off
	v_cvt_pk_bf16_f32 v134, v151, v152
	v_cvt_pk_bf16_f32 v135, v136, v137
	global_store_dwordx2 v[140:141], v[134:135], off
	s_nop 0
	v_add_u32_e32 v140, s4, v146
	v_ashrrev_i32_e32 v141, 31, v140
	v_mul_f32_e32 v133, v30, v130
	v_mul_f32_e32 v139, v31, v130
	v_mul_f32_e32 v147, v32, v130
	v_mul_f32_e32 v150, v33, v130
	v_mul_f32_e32 v151, v54, v131
	v_mul_f32_e32 v152, v55, v131
	v_lshlrev_b64 v[140:141], 14, v[140:141]
	v_mul_f32_e32 v153, v56, v131
	v_mul_f32_e32 v157, v57, v131
	v_lshl_add_u64 v[148:149], v[142:143], 0, v[140:141]
	v_lshl_add_u64 v[140:141], v[144:145], 0, v[140:141]
	s_nop 0
	v_mul_f32_e32 v133, v133, v202
	v_mul_f32_e32 v139, v139, v203
	v_mul_f32_e32 v147, v147, v204
	v_mul_f32_e32 v150, v150, v205
	v_mul_f32_e32 v151, v151, v202
	v_mul_f32_e32 v152, v152, v203
	v_cvt_pk_bf16_f32 v134, v133, v139
	v_cvt_pk_bf16_f32 v135, v147, v150
	v_mul_f32_e32 v136, v153, v204
	v_mul_f32_e32 v137, v157, v205
	global_store_dwordx2 v[148:149], v[134:135], off
	v_cvt_pk_bf16_f32 v134, v151, v152
	v_cvt_pk_bf16_f32 v135, v136, v137
	global_store_dwordx2 v[140:141], v[134:135], off
	s_nop 0
	v_add_u32_e32 v140, s4, v138
	v_ashrrev_i32_e32 v141, 31, v140
	v_mul_f32_e32 v133, v42, v130
	v_mul_f32_e32 v139, v43, v130
	v_mul_f32_e32 v147, v44, v130
	v_mul_f32_e32 v150, v45, v130
	v_mul_f32_e32 v151, v66, v131
	v_mul_f32_e32 v152, v67, v131
	v_lshlrev_b64 v[140:141], 14, v[140:141]
	v_mul_f32_e32 v153, v68, v131
	v_mul_f32_e32 v157, v69, v131
	v_lshl_add_u64 v[148:149], v[142:143], 0, v[140:141]
	v_lshl_add_u64 v[140:141], v[144:145], 0, v[140:141]
	s_nop 0
	v_mul_f32_e32 v133, v133, v206
	v_mul_f32_e32 v139, v139, v207
	v_mul_f32_e32 v147, v147, v208
	v_mul_f32_e32 v150, v150, v209
	v_mul_f32_e32 v151, v151, v206
	v_mul_f32_e32 v152, v152, v207
	v_cvt_pk_bf16_f32 v134, v133, v139
	v_cvt_pk_bf16_f32 v135, v147, v150
	v_mul_f32_e32 v136, v153, v208
	v_mul_f32_e32 v137, v157, v209
	global_store_dwordx2 v[148:149], v[134:135], off
	v_cvt_pk_bf16_f32 v134, v151, v152
	v_cvt_pk_bf16_f32 v135, v136, v137
	global_store_dwordx2 v[140:141], v[134:135], off
	s_nop 0
	v_mul_f32_e32 v133, v58, v130
	v_mul_f32_e32 v139, v59, v130
	v_mul_f32_e32 v147, v60, v130
	v_mul_f32_e32 v148, v61, v130
	v_add_u32_e32 v130, s4, v132
	v_mul_f32_e32 v149, v82, v131
	v_mul_f32_e32 v150, v83, v131
	v_mul_f32_e32 v151, v84, v131
	v_mul_f32_e32 v152, v85, v131
	v_ashrrev_i32_e32 v131, 31, v130
	v_lshlrev_b64 v[130:131], 14, v[130:131]
	v_lshl_add_u64 v[140:141], v[142:143], 0, v[130:131]
	v_lshl_add_u64 v[130:131], v[144:145], 0, v[130:131]
	s_nop 0
	v_mul_f32_e32 v133, v133, v210
	v_mul_f32_e32 v139, v139, v211
	v_mul_f32_e32 v142, v147, v212
	v_mul_f32_e32 v143, v148, v213
	v_mul_f32_e32 v147, v149, v210
	v_mul_f32_e32 v148, v150, v211
	v_cvt_pk_bf16_f32 v134, v133, v139
	v_cvt_pk_bf16_f32 v135, v142, v143
	v_mul_f32_e32 v136, v151, v212
	v_mul_f32_e32 v137, v152, v213
	global_store_dwordx2 v[140:141], v[134:135], off
	v_cvt_pk_bf16_f32 v134, v147, v148
	v_cvt_pk_bf16_f32 v135, v136, v137
	global_store_dwordx2 v[130:131], v[134:135], off
	s_andn2_b64 vcc, exec, s[54:55]
	s_cbranch_vccnz .LBB0_45
